# prologue pooling-fold accumulation loop hand-pipelined (16 loads per block, next block in flight)
# speedup vs baseline: 1.0211x; 1.0211x over previous
.LBB0_865:
	s_movk_i32 s82, 0x2000
	s_mov_b32 s14, 0
	v_lshl_add_u64 v[40:41], v[2:3], 0, s[12:13]
	global_load_dword v100, v[40:41], off
	v_lshl_add_u64 v[40:41], v[40:41], 0, s[82:83]
	global_load_dword v101, v[40:41], off offset:-4096
	global_load_dword v102, v[40:41], off
	v_lshl_add_u64 v[40:41], v[40:41], 0, s[82:83]
	global_load_dword v103, v[40:41], off offset:-4096
	global_load_dword v104, v[40:41], off
	v_lshl_add_u64 v[40:41], v[40:41], 0, s[82:83]
	global_load_dword v105, v[40:41], off offset:-4096
	global_load_dword v106, v[40:41], off
	v_lshl_add_u64 v[40:41], v[40:41], 0, s[82:83]
	global_load_dword v107, v[40:41], off offset:-4096
	global_load_dword v108, v[40:41], off
	v_lshl_add_u64 v[40:41], v[40:41], 0, s[82:83]
	global_load_dword v109, v[40:41], off offset:-4096
	global_load_dword v110, v[40:41], off
	v_lshl_add_u64 v[40:41], v[40:41], 0, s[82:83]
	global_load_dword v111, v[40:41], off offset:-4096
	global_load_dword v112, v[40:41], off
	v_lshl_add_u64 v[40:41], v[40:41], 0, s[82:83]
	global_load_dword v113, v[40:41], off offset:-4096
	global_load_dword v114, v[40:41], off
	v_lshl_add_u64 v[40:41], v[40:41], 0, s[82:83]
	global_load_dword v115, v[40:41], off offset:-4096
	ds_read_b128 v[28:31], v26
	ds_read_b128 v[34:37], v26 offset:16
.Lpf_loop:
	s_add_u32 s12, s12, 0x10000
	s_addc_u32 s13, s13, 0
	v_lshl_add_u64 v[40:41], v[2:3], 0, s[12:13]
	global_load_dword v116, v[40:41], off
	v_lshl_add_u64 v[40:41], v[40:41], 0, s[82:83]
	global_load_dword v117, v[40:41], off offset:-4096
	global_load_dword v118, v[40:41], off
	v_lshl_add_u64 v[40:41], v[40:41], 0, s[82:83]
	global_load_dword v119, v[40:41], off offset:-4096
	global_load_dword v120, v[40:41], off
	v_lshl_add_u64 v[40:41], v[40:41], 0, s[82:83]
	global_load_dword v121, v[40:41], off offset:-4096
	global_load_dword v122, v[40:41], off
	v_lshl_add_u64 v[40:41], v[40:41], 0, s[82:83]
	global_load_dword v123, v[40:41], off offset:-4096
	global_load_dword v124, v[40:41], off
	v_lshl_add_u64 v[40:41], v[40:41], 0, s[82:83]
	global_load_dword v125, v[40:41], off offset:-4096
	global_load_dword v126, v[40:41], off
	v_lshl_add_u64 v[40:41], v[40:41], 0, s[82:83]
	global_load_dword v127, v[40:41], off offset:-4096
	global_load_dword v128, v[40:41], off
	v_lshl_add_u64 v[40:41], v[40:41], 0, s[82:83]
	global_load_dword v129, v[40:41], off offset:-4096
	global_load_dword v130, v[40:41], off
	v_lshl_add_u64 v[40:41], v[40:41], 0, s[82:83]
	global_load_dword v131, v[40:41], off offset:-4096
	ds_read_b128 v[132:135], v26 offset:528
	ds_read_b128 v[136:139], v26 offset:544
	s_waitcnt vmcnt(31) lgkmcnt(2)
	v_pk_fma_f32 v[14:15], v[100:101], v[28:29], v[14:15] op_sel_hi:[0,1,1]
	v_pk_fma_f32 v[8:9], v[100:101], v[30:31], v[8:9] op_sel_hi:[0,1,1]
	v_pk_fma_f32 v[10:11], v[100:101], v[34:35], v[10:11] op_sel_hi:[0,1,1]
	v_pk_fma_f32 v[6:7], v[100:101], v[36:37], v[6:7] op_sel_hi:[0,1,1]
	ds_read_b128 v[28:31], v26 offset:1056
	ds_read_b128 v[34:37], v26 offset:1072
	s_waitcnt vmcnt(30) lgkmcnt(2)
	v_pk_fma_f32 v[14:15], v[100:101], v[132:133], v[14:15] op_sel:[1,0,0] op_sel_hi:[1,1,1]
	v_pk_fma_f32 v[8:9], v[100:101], v[134:135], v[8:9] op_sel:[1,0,0] op_sel_hi:[1,1,1]
	v_pk_fma_f32 v[10:11], v[100:101], v[136:137], v[10:11] op_sel:[1,0,0] op_sel_hi:[1,1,1]
	v_pk_fma_f32 v[6:7], v[100:101], v[138:139], v[6:7] op_sel:[1,0,0] op_sel_hi:[1,1,1]
	ds_read_b128 v[132:135], v26 offset:1584
	ds_read_b128 v[136:139], v26 offset:1600
	s_waitcnt vmcnt(29) lgkmcnt(2)
	v_pk_fma_f32 v[14:15], v[102:103], v[28:29], v[14:15] op_sel_hi:[0,1,1]
	v_pk_fma_f32 v[8:9], v[102:103], v[30:31], v[8:9] op_sel_hi:[0,1,1]
	v_pk_fma_f32 v[10:11], v[102:103], v[34:35], v[10:11] op_sel_hi:[0,1,1]
	v_pk_fma_f32 v[6:7], v[102:103], v[36:37], v[6:7] op_sel_hi:[0,1,1]
	ds_read_b128 v[28:31], v26 offset:2112
	ds_read_b128 v[34:37], v26 offset:2128
	s_waitcnt vmcnt(28) lgkmcnt(2)
	v_pk_fma_f32 v[14:15], v[102:103], v[132:133], v[14:15] op_sel:[1,0,0] op_sel_hi:[1,1,1]
	v_pk_fma_f32 v[8:9], v[102:103], v[134:135], v[8:9] op_sel:[1,0,0] op_sel_hi:[1,1,1]
	v_pk_fma_f32 v[10:11], v[102:103], v[136:137], v[10:11] op_sel:[1,0,0] op_sel_hi:[1,1,1]
	v_pk_fma_f32 v[6:7], v[102:103], v[138:139], v[6:7] op_sel:[1,0,0] op_sel_hi:[1,1,1]
	ds_read_b128 v[132:135], v26 offset:2640
	ds_read_b128 v[136:139], v26 offset:2656
	s_waitcnt vmcnt(27) lgkmcnt(2)
	v_pk_fma_f32 v[14:15], v[104:105], v[28:29], v[14:15] op_sel_hi:[0,1,1]
	v_pk_fma_f32 v[8:9], v[104:105], v[30:31], v[8:9] op_sel_hi:[0,1,1]
	v_pk_fma_f32 v[10:11], v[104:105], v[34:35], v[10:11] op_sel_hi:[0,1,1]
	v_pk_fma_f32 v[6:7], v[104:105], v[36:37], v[6:7] op_sel_hi:[0,1,1]
	ds_read_b128 v[28:31], v26 offset:3168
	ds_read_b128 v[34:37], v26 offset:3184
	s_waitcnt vmcnt(26) lgkmcnt(2)
	v_pk_fma_f32 v[14:15], v[104:105], v[132:133], v[14:15] op_sel:[1,0,0] op_sel_hi:[1,1,1]
	v_pk_fma_f32 v[8:9], v[104:105], v[134:135], v[8:9] op_sel:[1,0,0] op_sel_hi:[1,1,1]
	v_pk_fma_f32 v[10:11], v[104:105], v[136:137], v[10:11] op_sel:[1,0,0] op_sel_hi:[1,1,1]
	v_pk_fma_f32 v[6:7], v[104:105], v[138:139], v[6:7] op_sel:[1,0,0] op_sel_hi:[1,1,1]
	ds_read_b128 v[132:135], v26 offset:3696
	ds_read_b128 v[136:139], v26 offset:3712
	s_waitcnt vmcnt(25) lgkmcnt(2)
	v_pk_fma_f32 v[14:15], v[106:107], v[28:29], v[14:15] op_sel_hi:[0,1,1]
	v_pk_fma_f32 v[8:9], v[106:107], v[30:31], v[8:9] op_sel_hi:[0,1,1]
	v_pk_fma_f32 v[10:11], v[106:107], v[34:35], v[10:11] op_sel_hi:[0,1,1]
	v_pk_fma_f32 v[6:7], v[106:107], v[36:37], v[6:7] op_sel_hi:[0,1,1]
	ds_read_b128 v[28:31], v26 offset:4224
	ds_read_b128 v[34:37], v26 offset:4240
	s_waitcnt vmcnt(24) lgkmcnt(2)
	v_pk_fma_f32 v[14:15], v[106:107], v[132:133], v[14:15] op_sel:[1,0,0] op_sel_hi:[1,1,1]
	v_pk_fma_f32 v[8:9], v[106:107], v[134:135], v[8:9] op_sel:[1,0,0] op_sel_hi:[1,1,1]
	v_pk_fma_f32 v[10:11], v[106:107], v[136:137], v[10:11] op_sel:[1,0,0] op_sel_hi:[1,1,1]
	v_pk_fma_f32 v[6:7], v[106:107], v[138:139], v[6:7] op_sel:[1,0,0] op_sel_hi:[1,1,1]
	ds_read_b128 v[132:135], v26 offset:4752
	ds_read_b128 v[136:139], v26 offset:4768
	s_waitcnt vmcnt(23) lgkmcnt(2)
	v_pk_fma_f32 v[14:15], v[108:109], v[28:29], v[14:15] op_sel_hi:[0,1,1]
	v_pk_fma_f32 v[8:9], v[108:109], v[30:31], v[8:9] op_sel_hi:[0,1,1]
	v_pk_fma_f32 v[10:11], v[108:109], v[34:35], v[10:11] op_sel_hi:[0,1,1]
	v_pk_fma_f32 v[6:7], v[108:109], v[36:37], v[6:7] op_sel_hi:[0,1,1]
	ds_read_b128 v[28:31], v26 offset:5280
	ds_read_b128 v[34:37], v26 offset:5296
	s_waitcnt vmcnt(22) lgkmcnt(2)
	v_pk_fma_f32 v[14:15], v[108:109], v[132:133], v[14:15] op_sel:[1,0,0] op_sel_hi:[1,1,1]
	v_pk_fma_f32 v[8:9], v[108:109], v[134:135], v[8:9] op_sel:[1,0,0] op_sel_hi:[1,1,1]
	v_pk_fma_f32 v[10:11], v[108:109], v[136:137], v[10:11] op_sel:[1,0,0] op_sel_hi:[1,1,1]
	v_pk_fma_f32 v[6:7], v[108:109], v[138:139], v[6:7] op_sel:[1,0,0] op_sel_hi:[1,1,1]
	ds_read_b128 v[132:135], v26 offset:5808
	ds_read_b128 v[136:139], v26 offset:5824
	s_waitcnt vmcnt(21) lgkmcnt(2)
	v_pk_fma_f32 v[14:15], v[110:111], v[28:29], v[14:15] op_sel_hi:[0,1,1]
	v_pk_fma_f32 v[8:9], v[110:111], v[30:31], v[8:9] op_sel_hi:[0,1,1]
	v_pk_fma_f32 v[10:11], v[110:111], v[34:35], v[10:11] op_sel_hi:[0,1,1]
	v_pk_fma_f32 v[6:7], v[110:111], v[36:37], v[6:7] op_sel_hi:[0,1,1]
	ds_read_b128 v[28:31], v26 offset:6336
	ds_read_b128 v[34:37], v26 offset:6352
	s_waitcnt vmcnt(20) lgkmcnt(2)
	v_pk_fma_f32 v[14:15], v[110:111], v[132:133], v[14:15] op_sel:[1,0,0] op_sel_hi:[1,1,1]
	v_pk_fma_f32 v[8:9], v[110:111], v[134:135], v[8:9] op_sel:[1,0,0] op_sel_hi:[1,1,1]
	v_pk_fma_f32 v[10:11], v[110:111], v[136:137], v[10:11] op_sel:[1,0,0] op_sel_hi:[1,1,1]
	v_pk_fma_f32 v[6:7], v[110:111], v[138:139], v[6:7] op_sel:[1,0,0] op_sel_hi:[1,1,1]
	ds_read_b128 v[132:135], v26 offset:6864
	ds_read_b128 v[136:139], v26 offset:6880
	s_waitcnt vmcnt(19) lgkmcnt(2)
	v_pk_fma_f32 v[14:15], v[112:113], v[28:29], v[14:15] op_sel_hi:[0,1,1]
	v_pk_fma_f32 v[8:9], v[112:113], v[30:31], v[8:9] op_sel_hi:[0,1,1]
	v_pk_fma_f32 v[10:11], v[112:113], v[34:35], v[10:11] op_sel_hi:[0,1,1]
	v_pk_fma_f32 v[6:7], v[112:113], v[36:37], v[6:7] op_sel_hi:[0,1,1]
	ds_read_b128 v[28:31], v26 offset:7392
	ds_read_b128 v[34:37], v26 offset:7408
	s_waitcnt vmcnt(18) lgkmcnt(2)
	v_pk_fma_f32 v[14:15], v[112:113], v[132:133], v[14:15] op_sel:[1,0,0] op_sel_hi:[1,1,1]
	v_pk_fma_f32 v[8:9], v[112:113], v[134:135], v[8:9] op_sel:[1,0,0] op_sel_hi:[1,1,1]
	v_pk_fma_f32 v[10:11], v[112:113], v[136:137], v[10:11] op_sel:[1,0,0] op_sel_hi:[1,1,1]
	v_pk_fma_f32 v[6:7], v[112:113], v[138:139], v[6:7] op_sel:[1,0,0] op_sel_hi:[1,1,1]
	ds_read_b128 v[132:135], v26 offset:7920
	ds_read_b128 v[136:139], v26 offset:7936
	s_waitcnt vmcnt(17) lgkmcnt(2)
	v_pk_fma_f32 v[14:15], v[114:115], v[28:29], v[14:15] op_sel_hi:[0,1,1]
	v_pk_fma_f32 v[8:9], v[114:115], v[30:31], v[8:9] op_sel_hi:[0,1,1]
	v_pk_fma_f32 v[10:11], v[114:115], v[34:35], v[10:11] op_sel_hi:[0,1,1]
	v_pk_fma_f32 v[6:7], v[114:115], v[36:37], v[6:7] op_sel_hi:[0,1,1]
	ds_read_b128 v[28:31], v26 offset:8448
	ds_read_b128 v[34:37], v26 offset:8464
	s_waitcnt vmcnt(16) lgkmcnt(2)
	v_pk_fma_f32 v[14:15], v[114:115], v[132:133], v[14:15] op_sel:[1,0,0] op_sel_hi:[1,1,1]
	v_pk_fma_f32 v[8:9], v[114:115], v[134:135], v[8:9] op_sel:[1,0,0] op_sel_hi:[1,1,1]
	v_pk_fma_f32 v[10:11], v[114:115], v[136:137], v[10:11] op_sel:[1,0,0] op_sel_hi:[1,1,1]
	v_pk_fma_f32 v[6:7], v[114:115], v[138:139], v[6:7] op_sel:[1,0,0] op_sel_hi:[1,1,1]
	v_add_u32_e32 v26, 0x2100, v26
	s_cmp_eq_u32 s14, 3
	s_cbranch_scc1 .Lpf_last
	s_add_u32 s12, s12, 0x10000
	s_addc_u32 s13, s13, 0
	v_lshl_add_u64 v[40:41], v[2:3], 0, s[12:13]
	global_load_dword v100, v[40:41], off
	v_lshl_add_u64 v[40:41], v[40:41], 0, s[82:83]
	global_load_dword v101, v[40:41], off offset:-4096
	global_load_dword v102, v[40:41], off
	v_lshl_add_u64 v[40:41], v[40:41], 0, s[82:83]
	global_load_dword v103, v[40:41], off offset:-4096
	global_load_dword v104, v[40:41], off
	v_lshl_add_u64 v[40:41], v[40:41], 0, s[82:83]
	global_load_dword v105, v[40:41], off offset:-4096
	global_load_dword v106, v[40:41], off
	v_lshl_add_u64 v[40:41], v[40:41], 0, s[82:83]
	global_load_dword v107, v[40:41], off offset:-4096
	global_load_dword v108, v[40:41], off
	v_lshl_add_u64 v[40:41], v[40:41], 0, s[82:83]
	global_load_dword v109, v[40:41], off offset:-4096
	global_load_dword v110, v[40:41], off
	v_lshl_add_u64 v[40:41], v[40:41], 0, s[82:83]
	global_load_dword v111, v[40:41], off offset:-4096
	global_load_dword v112, v[40:41], off
	v_lshl_add_u64 v[40:41], v[40:41], 0, s[82:83]
	global_load_dword v113, v[40:41], off offset:-4096
	global_load_dword v114, v[40:41], off
	v_lshl_add_u64 v[40:41], v[40:41], 0, s[82:83]
	global_load_dword v115, v[40:41], off offset:-4096
	ds_read_b128 v[132:135], v26 offset:528
	ds_read_b128 v[136:139], v26 offset:544
	s_waitcnt vmcnt(31) lgkmcnt(2)
	v_pk_fma_f32 v[14:15], v[116:117], v[28:29], v[14:15] op_sel_hi:[0,1,1]
	v_pk_fma_f32 v[8:9], v[116:117], v[30:31], v[8:9] op_sel_hi:[0,1,1]
	v_pk_fma_f32 v[10:11], v[116:117], v[34:35], v[10:11] op_sel_hi:[0,1,1]
	v_pk_fma_f32 v[6:7], v[116:117], v[36:37], v[6:7] op_sel_hi:[0,1,1]
	ds_read_b128 v[28:31], v26 offset:1056
	ds_read_b128 v[34:37], v26 offset:1072
	s_waitcnt vmcnt(30) lgkmcnt(2)
	v_pk_fma_f32 v[14:15], v[116:117], v[132:133], v[14:15] op_sel:[1,0,0] op_sel_hi:[1,1,1]
	v_pk_fma_f32 v[8:9], v[116:117], v[134:135], v[8:9] op_sel:[1,0,0] op_sel_hi:[1,1,1]
	v_pk_fma_f32 v[10:11], v[116:117], v[136:137], v[10:11] op_sel:[1,0,0] op_sel_hi:[1,1,1]
	v_pk_fma_f32 v[6:7], v[116:117], v[138:139], v[6:7] op_sel:[1,0,0] op_sel_hi:[1,1,1]
	ds_read_b128 v[132:135], v26 offset:1584
	ds_read_b128 v[136:139], v26 offset:1600
	s_waitcnt vmcnt(29) lgkmcnt(2)
	v_pk_fma_f32 v[14:15], v[118:119], v[28:29], v[14:15] op_sel_hi:[0,1,1]
	v_pk_fma_f32 v[8:9], v[118:119], v[30:31], v[8:9] op_sel_hi:[0,1,1]
	v_pk_fma_f32 v[10:11], v[118:119], v[34:35], v[10:11] op_sel_hi:[0,1,1]
	v_pk_fma_f32 v[6:7], v[118:119], v[36:37], v[6:7] op_sel_hi:[0,1,1]
	ds_read_b128 v[28:31], v26 offset:2112
	ds_read_b128 v[34:37], v26 offset:2128
	s_waitcnt vmcnt(28) lgkmcnt(2)
	v_pk_fma_f32 v[14:15], v[118:119], v[132:133], v[14:15] op_sel:[1,0,0] op_sel_hi:[1,1,1]
	v_pk_fma_f32 v[8:9], v[118:119], v[134:135], v[8:9] op_sel:[1,0,0] op_sel_hi:[1,1,1]
	v_pk_fma_f32 v[10:11], v[118:119], v[136:137], v[10:11] op_sel:[1,0,0] op_sel_hi:[1,1,1]
	v_pk_fma_f32 v[6:7], v[118:119], v[138:139], v[6:7] op_sel:[1,0,0] op_sel_hi:[1,1,1]
	ds_read_b128 v[132:135], v26 offset:2640
	ds_read_b128 v[136:139], v26 offset:2656
	s_waitcnt vmcnt(27) lgkmcnt(2)
	v_pk_fma_f32 v[14:15], v[120:121], v[28:29], v[14:15] op_sel_hi:[0,1,1]
	v_pk_fma_f32 v[8:9], v[120:121], v[30:31], v[8:9] op_sel_hi:[0,1,1]
	v_pk_fma_f32 v[10:11], v[120:121], v[34:35], v[10:11] op_sel_hi:[0,1,1]
	v_pk_fma_f32 v[6:7], v[120:121], v[36:37], v[6:7] op_sel_hi:[0,1,1]
	ds_read_b128 v[28:31], v26 offset:3168
	ds_read_b128 v[34:37], v26 offset:3184
	s_waitcnt vmcnt(26) lgkmcnt(2)
	v_pk_fma_f32 v[14:15], v[120:121], v[132:133], v[14:15] op_sel:[1,0,0] op_sel_hi:[1,1,1]
	v_pk_fma_f32 v[8:9], v[120:121], v[134:135], v[8:9] op_sel:[1,0,0] op_sel_hi:[1,1,1]
	v_pk_fma_f32 v[10:11], v[120:121], v[136:137], v[10:11] op_sel:[1,0,0] op_sel_hi:[1,1,1]
	v_pk_fma_f32 v[6:7], v[120:121], v[138:139], v[6:7] op_sel:[1,0,0] op_sel_hi:[1,1,1]
	ds_read_b128 v[132:135], v26 offset:3696
	ds_read_b128 v[136:139], v26 offset:3712
	s_waitcnt vmcnt(25) lgkmcnt(2)
	v_pk_fma_f32 v[14:15], v[122:123], v[28:29], v[14:15] op_sel_hi:[0,1,1]
	v_pk_fma_f32 v[8:9], v[122:123], v[30:31], v[8:9] op_sel_hi:[0,1,1]
	v_pk_fma_f32 v[10:11], v[122:123], v[34:35], v[10:11] op_sel_hi:[0,1,1]
	v_pk_fma_f32 v[6:7], v[122:123], v[36:37], v[6:7] op_sel_hi:[0,1,1]
	ds_read_b128 v[28:31], v26 offset:4224
	ds_read_b128 v[34:37], v26 offset:4240
	s_waitcnt vmcnt(24) lgkmcnt(2)
	v_pk_fma_f32 v[14:15], v[122:123], v[132:133], v[14:15] op_sel:[1,0,0] op_sel_hi:[1,1,1]
	v_pk_fma_f32 v[8:9], v[122:123], v[134:135], v[8:9] op_sel:[1,0,0] op_sel_hi:[1,1,1]
	v_pk_fma_f32 v[10:11], v[122:123], v[136:137], v[10:11] op_sel:[1,0,0] op_sel_hi:[1,1,1]
	v_pk_fma_f32 v[6:7], v[122:123], v[138:139], v[6:7] op_sel:[1,0,0] op_sel_hi:[1,1,1]
	ds_read_b128 v[132:135], v26 offset:4752
	ds_read_b128 v[136:139], v26 offset:4768
	s_waitcnt vmcnt(23) lgkmcnt(2)
	v_pk_fma_f32 v[14:15], v[124:125], v[28:29], v[14:15] op_sel_hi:[0,1,1]
	v_pk_fma_f32 v[8:9], v[124:125], v[30:31], v[8:9] op_sel_hi:[0,1,1]
	v_pk_fma_f32 v[10:11], v[124:125], v[34:35], v[10:11] op_sel_hi:[0,1,1]
	v_pk_fma_f32 v[6:7], v[124:125], v[36:37], v[6:7] op_sel_hi:[0,1,1]
	ds_read_b128 v[28:31], v26 offset:5280
	ds_read_b128 v[34:37], v26 offset:5296
	s_waitcnt vmcnt(22) lgkmcnt(2)
	v_pk_fma_f32 v[14:15], v[124:125], v[132:133], v[14:15] op_sel:[1,0,0] op_sel_hi:[1,1,1]
	v_pk_fma_f32 v[8:9], v[124:125], v[134:135], v[8:9] op_sel:[1,0,0] op_sel_hi:[1,1,1]
	v_pk_fma_f32 v[10:11], v[124:125], v[136:137], v[10:11] op_sel:[1,0,0] op_sel_hi:[1,1,1]
	v_pk_fma_f32 v[6:7], v[124:125], v[138:139], v[6:7] op_sel:[1,0,0] op_sel_hi:[1,1,1]
	ds_read_b128 v[132:135], v26 offset:5808
	ds_read_b128 v[136:139], v26 offset:5824
	s_waitcnt vmcnt(21) lgkmcnt(2)
	v_pk_fma_f32 v[14:15], v[126:127], v[28:29], v[14:15] op_sel_hi:[0,1,1]
	v_pk_fma_f32 v[8:9], v[126:127], v[30:31], v[8:9] op_sel_hi:[0,1,1]
	v_pk_fma_f32 v[10:11], v[126:127], v[34:35], v[10:11] op_sel_hi:[0,1,1]
	v_pk_fma_f32 v[6:7], v[126:127], v[36:37], v[6:7] op_sel_hi:[0,1,1]
	ds_read_b128 v[28:31], v26 offset:6336
	ds_read_b128 v[34:37], v26 offset:6352
	s_waitcnt vmcnt(20) lgkmcnt(2)
	v_pk_fma_f32 v[14:15], v[126:127], v[132:133], v[14:15] op_sel:[1,0,0] op_sel_hi:[1,1,1]
	v_pk_fma_f32 v[8:9], v[126:127], v[134:135], v[8:9] op_sel:[1,0,0] op_sel_hi:[1,1,1]
	v_pk_fma_f32 v[10:11], v[126:127], v[136:137], v[10:11] op_sel:[1,0,0] op_sel_hi:[1,1,1]
	v_pk_fma_f32 v[6:7], v[126:127], v[138:139], v[6:7] op_sel:[1,0,0] op_sel_hi:[1,1,1]
	ds_read_b128 v[132:135], v26 offset:6864
	ds_read_b128 v[136:139], v26 offset:6880
	s_waitcnt vmcnt(19) lgkmcnt(2)
	v_pk_fma_f32 v[14:15], v[128:129], v[28:29], v[14:15] op_sel_hi:[0,1,1]
	v_pk_fma_f32 v[8:9], v[128:129], v[30:31], v[8:9] op_sel_hi:[0,1,1]
	v_pk_fma_f32 v[10:11], v[128:129], v[34:35], v[10:11] op_sel_hi:[0,1,1]
	v_pk_fma_f32 v[6:7], v[128:129], v[36:37], v[6:7] op_sel_hi:[0,1,1]
	ds_read_b128 v[28:31], v26 offset:7392
	ds_read_b128 v[34:37], v26 offset:7408
	s_waitcnt vmcnt(18) lgkmcnt(2)
	v_pk_fma_f32 v[14:15], v[128:129], v[132:133], v[14:15] op_sel:[1,0,0] op_sel_hi:[1,1,1]
	v_pk_fma_f32 v[8:9], v[128:129], v[134:135], v[8:9] op_sel:[1,0,0] op_sel_hi:[1,1,1]
	v_pk_fma_f32 v[10:11], v[128:129], v[136:137], v[10:11] op_sel:[1,0,0] op_sel_hi:[1,1,1]
	v_pk_fma_f32 v[6:7], v[128:129], v[138:139], v[6:7] op_sel:[1,0,0] op_sel_hi:[1,1,1]
	ds_read_b128 v[132:135], v26 offset:7920
	ds_read_b128 v[136:139], v26 offset:7936
	s_waitcnt vmcnt(17) lgkmcnt(2)
	v_pk_fma_f32 v[14:15], v[130:131], v[28:29], v[14:15] op_sel_hi:[0,1,1]
	v_pk_fma_f32 v[8:9], v[130:131], v[30:31], v[8:9] op_sel_hi:[0,1,1]
	v_pk_fma_f32 v[10:11], v[130:131], v[34:35], v[10:11] op_sel_hi:[0,1,1]
	v_pk_fma_f32 v[6:7], v[130:131], v[36:37], v[6:7] op_sel_hi:[0,1,1]
	ds_read_b128 v[28:31], v26 offset:8448
	ds_read_b128 v[34:37], v26 offset:8464
	s_waitcnt vmcnt(16) lgkmcnt(2)
	v_pk_fma_f32 v[14:15], v[130:131], v[132:133], v[14:15] op_sel:[1,0,0] op_sel_hi:[1,1,1]
	v_pk_fma_f32 v[8:9], v[130:131], v[134:135], v[8:9] op_sel:[1,0,0] op_sel_hi:[1,1,1]
	v_pk_fma_f32 v[10:11], v[130:131], v[136:137], v[10:11] op_sel:[1,0,0] op_sel_hi:[1,1,1]
	v_pk_fma_f32 v[6:7], v[130:131], v[138:139], v[6:7] op_sel:[1,0,0] op_sel_hi:[1,1,1]
	v_add_u32_e32 v26, 0x2100, v26
	s_add_i32 s14, s14, 1
	s_branch .Lpf_loop
.Lpf_last:
	ds_read_b128 v[132:135], v26 offset:528
	ds_read_b128 v[136:139], v26 offset:544
	s_waitcnt vmcnt(15) lgkmcnt(2)
	v_pk_fma_f32 v[14:15], v[116:117], v[28:29], v[14:15] op_sel_hi:[0,1,1]
	v_pk_fma_f32 v[8:9], v[116:117], v[30:31], v[8:9] op_sel_hi:[0,1,1]
	v_pk_fma_f32 v[10:11], v[116:117], v[34:35], v[10:11] op_sel_hi:[0,1,1]
	v_pk_fma_f32 v[6:7], v[116:117], v[36:37], v[6:7] op_sel_hi:[0,1,1]
	ds_read_b128 v[28:31], v26 offset:1056
	ds_read_b128 v[34:37], v26 offset:1072
	s_waitcnt vmcnt(14) lgkmcnt(2)
	v_pk_fma_f32 v[14:15], v[116:117], v[132:133], v[14:15] op_sel:[1,0,0] op_sel_hi:[1,1,1]
	v_pk_fma_f32 v[8:9], v[116:117], v[134:135], v[8:9] op_sel:[1,0,0] op_sel_hi:[1,1,1]
	v_pk_fma_f32 v[10:11], v[116:117], v[136:137], v[10:11] op_sel:[1,0,0] op_sel_hi:[1,1,1]
	v_pk_fma_f32 v[6:7], v[116:117], v[138:139], v[6:7] op_sel:[1,0,0] op_sel_hi:[1,1,1]
	ds_read_b128 v[132:135], v26 offset:1584
	ds_read_b128 v[136:139], v26 offset:1600
	s_waitcnt vmcnt(13) lgkmcnt(2)
	v_pk_fma_f32 v[14:15], v[118:119], v[28:29], v[14:15] op_sel_hi:[0,1,1]
	v_pk_fma_f32 v[8:9], v[118:119], v[30:31], v[8:9] op_sel_hi:[0,1,1]
	v_pk_fma_f32 v[10:11], v[118:119], v[34:35], v[10:11] op_sel_hi:[0,1,1]
	v_pk_fma_f32 v[6:7], v[118:119], v[36:37], v[6:7] op_sel_hi:[0,1,1]
	ds_read_b128 v[28:31], v26 offset:2112
	ds_read_b128 v[34:37], v26 offset:2128
	s_waitcnt vmcnt(12) lgkmcnt(2)
	v_pk_fma_f32 v[14:15], v[118:119], v[132:133], v[14:15] op_sel:[1,0,0] op_sel_hi:[1,1,1]
	v_pk_fma_f32 v[8:9], v[118:119], v[134:135], v[8:9] op_sel:[1,0,0] op_sel_hi:[1,1,1]
	v_pk_fma_f32 v[10:11], v[118:119], v[136:137], v[10:11] op_sel:[1,0,0] op_sel_hi:[1,1,1]
	v_pk_fma_f32 v[6:7], v[118:119], v[138:139], v[6:7] op_sel:[1,0,0] op_sel_hi:[1,1,1]
	ds_read_b128 v[132:135], v26 offset:2640
	ds_read_b128 v[136:139], v26 offset:2656
	s_waitcnt vmcnt(11) lgkmcnt(2)
	v_pk_fma_f32 v[14:15], v[120:121], v[28:29], v[14:15] op_sel_hi:[0,1,1]
	v_pk_fma_f32 v[8:9], v[120:121], v[30:31], v[8:9] op_sel_hi:[0,1,1]
	v_pk_fma_f32 v[10:11], v[120:121], v[34:35], v[10:11] op_sel_hi:[0,1,1]
	v_pk_fma_f32 v[6:7], v[120:121], v[36:37], v[6:7] op_sel_hi:[0,1,1]
	ds_read_b128 v[28:31], v26 offset:3168
	ds_read_b128 v[34:37], v26 offset:3184
	s_waitcnt vmcnt(10) lgkmcnt(2)
	v_pk_fma_f32 v[14:15], v[120:121], v[132:133], v[14:15] op_sel:[1,0,0] op_sel_hi:[1,1,1]
	v_pk_fma_f32 v[8:9], v[120:121], v[134:135], v[8:9] op_sel:[1,0,0] op_sel_hi:[1,1,1]
	v_pk_fma_f32 v[10:11], v[120:121], v[136:137], v[10:11] op_sel:[1,0,0] op_sel_hi:[1,1,1]
	v_pk_fma_f32 v[6:7], v[120:121], v[138:139], v[6:7] op_sel:[1,0,0] op_sel_hi:[1,1,1]
	ds_read_b128 v[132:135], v26 offset:3696
	ds_read_b128 v[136:139], v26 offset:3712
	s_waitcnt vmcnt(9) lgkmcnt(2)
	v_pk_fma_f32 v[14:15], v[122:123], v[28:29], v[14:15] op_sel_hi:[0,1,1]
	v_pk_fma_f32 v[8:9], v[122:123], v[30:31], v[8:9] op_sel_hi:[0,1,1]
	v_pk_fma_f32 v[10:11], v[122:123], v[34:35], v[10:11] op_sel_hi:[0,1,1]
	v_pk_fma_f32 v[6:7], v[122:123], v[36:37], v[6:7] op_sel_hi:[0,1,1]
	ds_read_b128 v[28:31], v26 offset:4224
	ds_read_b128 v[34:37], v26 offset:4240
	s_waitcnt vmcnt(8) lgkmcnt(2)
	v_pk_fma_f32 v[14:15], v[122:123], v[132:133], v[14:15] op_sel:[1,0,0] op_sel_hi:[1,1,1]
	v_pk_fma_f32 v[8:9], v[122:123], v[134:135], v[8:9] op_sel:[1,0,0] op_sel_hi:[1,1,1]
	v_pk_fma_f32 v[10:11], v[122:123], v[136:137], v[10:11] op_sel:[1,0,0] op_sel_hi:[1,1,1]
	v_pk_fma_f32 v[6:7], v[122:123], v[138:139], v[6:7] op_sel:[1,0,0] op_sel_hi:[1,1,1]
	ds_read_b128 v[132:135], v26 offset:4752
	ds_read_b128 v[136:139], v26 offset:4768
	s_waitcnt vmcnt(7) lgkmcnt(2)
	v_pk_fma_f32 v[14:15], v[124:125], v[28:29], v[14:15] op_sel_hi:[0,1,1]
	v_pk_fma_f32 v[8:9], v[124:125], v[30:31], v[8:9] op_sel_hi:[0,1,1]
	v_pk_fma_f32 v[10:11], v[124:125], v[34:35], v[10:11] op_sel_hi:[0,1,1]
	v_pk_fma_f32 v[6:7], v[124:125], v[36:37], v[6:7] op_sel_hi:[0,1,1]
	ds_read_b128 v[28:31], v26 offset:5280
	ds_read_b128 v[34:37], v26 offset:5296
	s_waitcnt vmcnt(6) lgkmcnt(2)
	v_pk_fma_f32 v[14:15], v[124:125], v[132:133], v[14:15] op_sel:[1,0,0] op_sel_hi:[1,1,1]
	v_pk_fma_f32 v[8:9], v[124:125], v[134:135], v[8:9] op_sel:[1,0,0] op_sel_hi:[1,1,1]
	v_pk_fma_f32 v[10:11], v[124:125], v[136:137], v[10:11] op_sel:[1,0,0] op_sel_hi:[1,1,1]
	v_pk_fma_f32 v[6:7], v[124:125], v[138:139], v[6:7] op_sel:[1,0,0] op_sel_hi:[1,1,1]
	ds_read_b128 v[132:135], v26 offset:5808
	ds_read_b128 v[136:139], v26 offset:5824
	s_waitcnt vmcnt(5) lgkmcnt(2)
	v_pk_fma_f32 v[14:15], v[126:127], v[28:29], v[14:15] op_sel_hi:[0,1,1]
	v_pk_fma_f32 v[8:9], v[126:127], v[30:31], v[8:9] op_sel_hi:[0,1,1]
	v_pk_fma_f32 v[10:11], v[126:127], v[34:35], v[10:11] op_sel_hi:[0,1,1]
	v_pk_fma_f32 v[6:7], v[126:127], v[36:37], v[6:7] op_sel_hi:[0,1,1]
	ds_read_b128 v[28:31], v26 offset:6336
	ds_read_b128 v[34:37], v26 offset:6352
	s_waitcnt vmcnt(4) lgkmcnt(2)
	v_pk_fma_f32 v[14:15], v[126:127], v[132:133], v[14:15] op_sel:[1,0,0] op_sel_hi:[1,1,1]
	v_pk_fma_f32 v[8:9], v[126:127], v[134:135], v[8:9] op_sel:[1,0,0] op_sel_hi:[1,1,1]
	v_pk_fma_f32 v[10:11], v[126:127], v[136:137], v[10:11] op_sel:[1,0,0] op_sel_hi:[1,1,1]
	v_pk_fma_f32 v[6:7], v[126:127], v[138:139], v[6:7] op_sel:[1,0,0] op_sel_hi:[1,1,1]
	ds_read_b128 v[132:135], v26 offset:6864
	ds_read_b128 v[136:139], v26 offset:6880
	s_waitcnt vmcnt(3) lgkmcnt(2)
	v_pk_fma_f32 v[14:15], v[128:129], v[28:29], v[14:15] op_sel_hi:[0,1,1]
	v_pk_fma_f32 v[8:9], v[128:129], v[30:31], v[8:9] op_sel_hi:[0,1,1]
	v_pk_fma_f32 v[10:11], v[128:129], v[34:35], v[10:11] op_sel_hi:[0,1,1]
	v_pk_fma_f32 v[6:7], v[128:129], v[36:37], v[6:7] op_sel_hi:[0,1,1]
	ds_read_b128 v[28:31], v26 offset:7392
	ds_read_b128 v[34:37], v26 offset:7408
	s_waitcnt vmcnt(2) lgkmcnt(2)
	v_pk_fma_f32 v[14:15], v[128:129], v[132:133], v[14:15] op_sel:[1,0,0] op_sel_hi:[1,1,1]
	v_pk_fma_f32 v[8:9], v[128:129], v[134:135], v[8:9] op_sel:[1,0,0] op_sel_hi:[1,1,1]
	v_pk_fma_f32 v[10:11], v[128:129], v[136:137], v[10:11] op_sel:[1,0,0] op_sel_hi:[1,1,1]
	v_pk_fma_f32 v[6:7], v[128:129], v[138:139], v[6:7] op_sel:[1,0,0] op_sel_hi:[1,1,1]
	ds_read_b128 v[132:135], v26 offset:7920
	ds_read_b128 v[136:139], v26 offset:7936
	s_waitcnt vmcnt(1) lgkmcnt(2)
	v_pk_fma_f32 v[14:15], v[130:131], v[28:29], v[14:15] op_sel_hi:[0,1,1]
	v_pk_fma_f32 v[8:9], v[130:131], v[30:31], v[8:9] op_sel_hi:[0,1,1]
	v_pk_fma_f32 v[10:11], v[130:131], v[34:35], v[10:11] op_sel_hi:[0,1,1]
	v_pk_fma_f32 v[6:7], v[130:131], v[36:37], v[6:7] op_sel_hi:[0,1,1]
	s_waitcnt vmcnt(0) lgkmcnt(0)
	v_pk_fma_f32 v[14:15], v[130:131], v[132:133], v[14:15] op_sel:[1,0,0] op_sel_hi:[1,1,1]
	v_pk_fma_f32 v[8:9], v[130:131], v[134:135], v[8:9] op_sel:[1,0,0] op_sel_hi:[1,1,1]
	v_pk_fma_f32 v[10:11], v[130:131], v[136:137], v[10:11] op_sel:[1,0,0] op_sel_hi:[1,1,1]
	v_pk_fma_f32 v[6:7], v[130:131], v[138:139], v[6:7] op_sel:[1,0,0] op_sel_hi:[1,1,1]
	s_lshl_b32 s12, s33, 5
	s_and_b32 s12, s12, 0x3e0
	v_or_b32_e32 v2, s12, v38
	s_lshl_b64 s[12:13], s[18:19], 22
	s_add_u32 s12, s34, s12
	s_addc_u32 s13, s35, s13
	v_lshlrev_b32_e32 v192, 12, v2
	v_lshl_add_u64 v[2:3], s[12:13], 0, v[192:193]
	s_lshl_b32 s82, s37, 1
	v_readlane_b32 s12, v250, 21
	v_lshl_add_u64 v[2:3], v[2:3], 0, s[82:83]
	s_add_i32 s33, s33, s70
	s_add_i32 s36, s36, s12
	v_lshl_add_u64 v[12:13], v[0:1], 1, v[2:3]
	v_cvt_pk_bf16_f32 v2, v14, v15
	v_cvt_pk_bf16_f32 v3, v8, v9
	v_cvt_pk_bf16_f32 v4, v10, v11
	v_cvt_pk_bf16_f32 v5, v6, v7
	s_cmpk_gt_i32 s33, 0xff
	global_store_dwordx4 v[12:13], v[2:5], off
	s_cbranch_scc0 .LBB0_846
	v_readlane_b32 s36, v253, 8
	v_readlane_b32 s42, v253, 14
	v_readlane_b32 s43, v253, 15
	v_readlane_b32 s37, v253, 9
	v_readlane_b32 s38, v253, 10
	v_readlane_b32 s39, v253, 11
	v_readlane_b32 s40, v253, 12
	v_readlane_b32 s41, v253, 13
	s_branch .LBB0_721
